# attention row-max: 19-deep serial v_max chain replaced by 4 interleaved v_max3 chains (depth 6, bit-identical); no pacing sleep
# speedup vs baseline: 1.0081x; 1.0029x over previous
; DI void attn_phase(ldsp lds, const bf16_t* Q, const bf16_t* KN, const bf16_t* KR, const bf16_t* VT, bf16_t* O, int vcu, int G) {
;     ...
;                     float mx = s0[0];
; #pragma unroll
;                     for (int r = 1; r < 16; ++r) mx = fmaxf(mx, s0[r]);
; #pragma unroll
;                     for (int r = 0; r < 16; ++r) mx = fmaxf(mx, s1[r]);
;                     { auto t_ = __builtin_amdgcn_permlane32_swap(__float_as_uint(mx), __float_as_uint(mx), false, false); mx = fmaxf(__uint_as_float(t_[0]), __uint_as_float(t_[1])); }
;                     if (__builtin_amdgcn_ballot_w64(mx - mrun > 8.0f) != 0ull) {
;                         const float mn = fmaxf(mrun, mx), al = __builtin_amdgcn_exp2f(mrun - mn); mrun = mn; lrun *= al;
; #pragma unroll
;                         for (int d = 0; d < 4; ++d)
; #pragma unroll
;                             for (int r = 0; r < 16; ++r) o[d][r] *= al;
;                     }
.LBB0_1456:
	s_nop 8
	v_max3_f32 v1, v82, v83, v84
	v_max3_f32 v230, v91, v92, v93
	v_max3_f32 v231, v66, v67, v68
	v_max3_f32 v252, v75, v76, v77
	v_max3_f32 v1, v1, v85, v86
	v_max3_f32 v230, v230, v94, v95
	v_max3_f32 v231, v231, v69, v70
	v_max3_f32 v252, v252, v78, v79
	v_max3_f32 v1, v1, v87, v88
	v_max3_f32 v230, v230, v96, v97
	v_max3_f32 v231, v231, v71, v72
	v_max3_f32 v252, v252, v80, v81
	v_max3_f32 v1, v1, v89, v90
	v_max3_f32 v231, v231, v73, v74
	v_max3_f32 v1, v1, v230, v252
	v_max_f32_e32 v1, v1, v231
	v_mov_b32_e32 v230, v1
	s_nop 1
	v_permlane32_swap_b32_e32 v1, v230
	v_max_f32_e32 v230, v230, v230
	v_max_f32_e32 v1, v1, v1
	v_max_f32_e32 v1, v1, v230
	v_sub_f32_e32 v230, v1, v229
	v_cmp_lt_f32_e32 vcc, s20, v230
	s_cbranch_vccz .LBB0_1458
	v_max_f32_e32 v1, v1, v1
	v_max_f32_e32 v230, v229, v229
	v_max_f32_e32 v1, v230, v1
	v_sub_f32_e32 v229, v229, v1
	v_exp_f32_e32 v230, v229
	v_mov_b32_e32 v229, v1
	v_pk_mul_f32 v[64:65], v[64:65], v[230:231] op_sel_hi:[1,0]
	v_pk_mul_f32 v[62:63], v[62:63], v[230:231] op_sel_hi:[1,0]
	v_pk_mul_f32 v[60:61], v[60:61], v[230:231] op_sel_hi:[1,0]
	v_pk_mul_f32 v[58:59], v[58:59], v[230:231] op_sel_hi:[1,0]
	v_pk_mul_f32 v[56:57], v[56:57], v[230:231] op_sel_hi:[1,0]
	v_pk_mul_f32 v[54:55], v[54:55], v[230:231] op_sel_hi:[1,0]
	v_pk_mul_f32 v[52:53], v[52:53], v[230:231] op_sel_hi:[1,0]
	v_pk_mul_f32 v[50:51], v[50:51], v[230:231] op_sel_hi:[1,0]
	v_pk_mul_f32 v[48:49], v[48:49], v[230:231] op_sel_hi:[1,0]
	v_pk_mul_f32 v[46:47], v[46:47], v[230:231] op_sel_hi:[1,0]
	v_pk_mul_f32 v[44:45], v[44:45], v[230:231] op_sel_hi:[1,0]
	v_pk_mul_f32 v[42:43], v[42:43], v[230:231] op_sel_hi:[1,0]
	v_pk_mul_f32 v[40:41], v[40:41], v[230:231] op_sel_hi:[1,0]
	v_pk_mul_f32 v[38:39], v[38:39], v[230:231] op_sel_hi:[1,0]
	v_pk_mul_f32 v[36:37], v[36:37], v[230:231] op_sel_hi:[1,0]
	v_pk_mul_f32 v[34:35], v[34:35], v[230:231] op_sel_hi:[1,0]
	v_pk_mul_f32 v[32:33], v[32:33], v[230:231] op_sel_hi:[1,0]
	v_pk_mul_f32 v[30:31], v[30:31], v[230:231] op_sel_hi:[1,0]
	v_pk_mul_f32 v[28:29], v[28:29], v[230:231] op_sel_hi:[1,0]
	v_pk_mul_f32 v[26:27], v[26:27], v[230:231] op_sel_hi:[1,0]
	v_pk_mul_f32 v[24:25], v[24:25], v[230:231] op_sel_hi:[1,0]
	v_pk_mul_f32 v[22:23], v[22:23], v[230:231] op_sel_hi:[1,0]
	v_pk_mul_f32 v[20:21], v[20:21], v[230:231] op_sel_hi:[1,0]
	v_pk_mul_f32 v[18:19], v[18:19], v[230:231] op_sel_hi:[1,0]
	v_pk_mul_f32 v[16:17], v[16:17], v[230:231] op_sel_hi:[1,0]
	v_pk_mul_f32 v[14:15], v[14:15], v[230:231] op_sel_hi:[1,0]
	v_pk_mul_f32 v[12:13], v[12:13], v[230:231] op_sel_hi:[1,0]
	v_pk_mul_f32 v[10:11], v[10:11], v[230:231] op_sel_hi:[1,0]
	v_pk_mul_f32 v[8:9], v[8:9], v[230:231] op_sel_hi:[1,0]
	v_pk_mul_f32 v[6:7], v[6:7], v[230:231] op_sel_hi:[1,0]
	v_pk_mul_f32 v[4:5], v[4:5], v[230:231] op_sel_hi:[1,0]
	v_pk_mul_f32 v[2:3], v[2:3], v[230:231] op_sel_hi:[1,0]
	v_mul_f32_e32 v227, v227, v230
